# DIR=1 SSD variant: the two 64-lane suffix scans interleaved (6 instead of 12 dependent bpermute round trips)
# baseline (speedup 1.0000x reference)
; __device__ __forceinline__ float lane_get(float v, int src_lane) { return __int_as_float(__builtin_amdgcn_ds_bpermute(src_lane << 2, __float_as_int(v))); }
; #define LDS_FENCE() asm volatile("s_waitcnt lgkmcnt(0)" ::: "memory")
; __device__ __forceinline__ float wave_suffix(float v, int lane) {
; #pragma unroll
;     for (int o = 1; o < 64; o <<= 1) { const float t = lane_get(v, (lane + o) & 63); if (lane + o < 64) v += t; }
;     return v;
; }
;     ...
;         if (DIR == 0) { const float p0 = wave_prefix(d0 * a_neg, lane); const float tot0 = __int_as_float(__builtin_amdgcn_readlane(__float_as_int(p0), 63)); const float p1 = wave_prefix(d1 * a_neg, lane) + tot0; c0 = p0; c1 = p1; ctot = __int_as_float(__builtin_amdgcn_readlane(__float_as_int(p1), 63)); }
;         else { const float s1 = wave_suffix(d1 * a_neg, lane); const float tot1 = __int_as_float(__builtin_amdgcn_readlane(__float_as_int(s1), 0)); const float s0 = wave_suffix(d0 * a_neg, lane) + tot1; c0 = s0; c1 = s1; ctot = __int_as_float(__builtin_amdgcn_readlane(__float_as_int(s0), 0)); }
;         cumL[lane] = c0; cumL[lane + 64] = c1; dtL[lane] = d0; dtL[lane + 64] = d1;
;         sclL[lane] = d0 * __expf(ctot - c0); sclL[lane + 64] = d1 * __expf(ctot - c1);
;         LDS_FENCE();
;         float mref[4];
;         if (DIR == 0) { mref[0] = 0.f; mref[1] = cumL[31]; mref[2] = cumL[63]; mref[3] = cumL[95]; }
;         else { mref[0] = cumL[32]; mref[1] = cumL[64]; mref[2] = cumL[96]; mref[3] = 0.f; }
; #pragma unroll
;         for (int ib = 0; ib < 4; ++ib) mref[ib] = __int_as_float(__builtin_amdgcn_readfirstlane(__float_as_int(mref[ib])));
;         if (!is_ctx) {
; #pragma unroll
;             for (int ib = 0; ib < 4; ++ib) { wL[ib * 128 + lane] = d0 * __expf(mref[ib] - c0); wL[ib * 128 + 64 + lane] = d1 * __expf(mref[ib] - c1); }
.LBB0_427:
	v_mul_f32_e64 v66, v64, -v141
	v_mul_f32_e64 v69, v65, -v141
	ds_bpermute_b32 v67, v111, v66
	ds_bpermute_b32 v68, v111, v69
	s_cmp_lt_u32 s52, 2
	s_cselect_b32 s33, 1, 17
	s_cselect_b32 s53, s39, s49
	s_sub_i32 s33, s33, s52
	s_waitcnt lgkmcnt(0)
	v_fma_f32 v67, v64, -v141, v67
	v_fma_f32 v68, v65, -v141, v68
	v_cndmask_b32_e64 v66, v67, v66, s[2:3]
	v_cndmask_b32_e64 v69, v68, v69, s[2:3]
	ds_bpermute_b32 v67, v117, v66
	ds_bpermute_b32 v68, v117, v69
	s_add_i32 s54, s33, s53
	v_mov_b32_e32 v70, s76
	s_ashr_i32 s55, s54, 31
	s_lshl_b64 s[54:55], s[54:55], 19
	s_waitcnt lgkmcnt(0)
	v_add_f32_e32 v67, v66, v67
	v_add_f32_e32 v68, v69, v68
	v_cndmask_b32_e64 v66, v66, v67, s[4:5]
	v_cndmask_b32_e64 v69, v69, v68, s[4:5]
	ds_bpermute_b32 v67, v158, v66
	ds_bpermute_b32 v68, v158, v69
	s_cmp_gt_u32 s52, 1
	v_lshl_add_u64 v[134:135], v[94:95], 0, s[54:55]
	v_lshlrev_b32_e32 v118, 1, v114
	v_mov_b32_e32 v119, 0
	v_lshl_add_u64 v[118:119], v[134:135], 0, v[118:119]
	global_load_dwordx4 v[176:179], v[118:119], off
	global_load_dwordx4 v[180:183], v[118:119], off offset:32
	global_load_dwordx4 v[184:187], v[118:119], off offset:64
	global_load_dwordx4 v[200:203], v[118:119], off offset:96
	global_load_dwordx4 v[204:207], v[118:119], off offset:128
	global_load_dwordx4 v[188:191], v[118:119], off offset:160
	global_load_dwordx4 v[228:231], v[118:119], off offset:192
	global_load_dwordx4 v[232:235], v[118:119], off offset:224
	s_waitcnt lgkmcnt(0)
	v_add_f32_e32 v67, v66, v67
	v_add_f32_e32 v68, v69, v68
	v_cndmask_b32_e64 v66, v66, v67, s[6:7]
	v_cndmask_b32_e64 v69, v69, v68, s[6:7]
	ds_bpermute_b32 v67, v159, v66
	ds_bpermute_b32 v68, v159, v69
	s_waitcnt lgkmcnt(0)
	v_add_f32_e32 v67, v66, v67
	v_add_f32_e32 v68, v69, v68
	v_cndmask_b32_e64 v66, v66, v67, s[8:9]
	v_cndmask_b32_e64 v69, v69, v68, s[8:9]
	ds_bpermute_b32 v67, v160, v66
	ds_bpermute_b32 v68, v160, v69
	s_waitcnt lgkmcnt(0)
	v_add_f32_e32 v67, v66, v67
	v_add_f32_e32 v68, v69, v68
	v_cndmask_b32_e64 v66, v66, v67, s[10:11]
	v_cndmask_b32_e64 v69, v69, v68, s[10:11]
	ds_bpermute_b32 v67, v161, v66
	ds_bpermute_b32 v68, v161, v69
	s_waitcnt lgkmcnt(0)
	v_add_f32_e32 v67, v66, v67
	v_add_f32_e32 v68, v69, v68
	v_cndmask_b32_e64 v66, v66, v67, s[12:13]
	v_cndmask_b32_e64 v69, v69, v68, s[12:13]
	s_nop 0
	v_readlane_b32 s53, v66, 0
	s_nop 1
	v_add_f32_e32 v67, s53, v69
	ds_write2st64_b32 v162, v67, v66 offset1:1
	ds_write2st64_b32 v162, v65, v64 offset0:2 offset1:3
	v_readlane_b32 s53, v67, 0
	s_nop 1
	v_sub_f32_e32 v68, s53, v67
	v_sub_f32_e32 v69, s53, v66
	v_mul_f32_e32 v68, 0x3fb8aa3b, v68
	v_mul_f32_e32 v69, 0x3fb8aa3b, v69
	v_exp_f32_e32 v68, v68
	v_exp_f32_e32 v69, v69
	v_mul_f32_e32 v68, v65, v68
	v_mul_f32_e32 v69, v64, v69
	ds_write2st64_b32 v162, v68, v69 offset0:4 offset1:5
	s_waitcnt lgkmcnt(0)
	ds_read2_b32 v[68:69], v70 offset0:32 offset1:64
	ds_read_b32 v70, v70 offset:384
	s_waitcnt lgkmcnt(0)
	v_readfirstlane_b32 s54, v68
	v_readfirstlane_b32 s55, v69
	s_waitcnt lgkmcnt(0)
	v_readfirstlane_b32 s96, v70
	s_cbranch_scc0 .Lssd_a_ctx
	v_sub_f32_e32 v68, s54, v67
	v_sub_f32_e32 v69, s54, v66
	v_mul_f32_e32 v68, 0x3fb8aa3b, v68
	v_mul_f32_e32 v69, 0x3fb8aa3b, v69
	v_exp_f32_e32 v68, v68
	v_exp_f32_e32 v69, v69
	s_andn2_b64 vcc, exec, s[30:31]
	s_mov_b32 s62, s40
	v_mul_f32_e32 v68, v65, v68
	v_mul_f32_e32 v69, v64, v69
	ds_write2st64_b32 v162, v68, v69 offset0:6 offset1:7
	v_sub_f32_e32 v68, s55, v67
	v_sub_f32_e32 v69, s55, v66
	v_mul_f32_e32 v68, 0x3fb8aa3b, v68
	v_mul_f32_e32 v69, 0x3fb8aa3b, v69
	v_exp_f32_e32 v68, v68
	v_exp_f32_e32 v69, v69
	v_mov_b32_e32 v80, v213
	s_mov_b32 s63, s93
	v_mul_f32_e32 v68, v65, v68
	v_mul_f32_e32 v69, v64, v69
	ds_write2st64_b32 v162, v68, v69 offset0:8 offset1:9
	v_sub_f32_e32 v68, s96, v67
	v_sub_f32_e32 v69, s96, v66
	v_mul_f32_e32 v68, 0x3fb8aa3b, v68
	v_mul_f32_e32 v69, 0x3fb8aa3b, v69
	v_mul_f32_e64 v67, -v67, s71
	v_mul_f32_e64 v66, -v66, s71
	v_exp_f32_e32 v68, v68
	v_exp_f32_e32 v69, v69
	v_exp_f32_e32 v67, v67
	v_exp_f32_e32 v66, v66
	v_mul_f32_e32 v68, v65, v68
	v_mul_f32_e32 v69, v64, v69
	v_mul_f32_e32 v65, v65, v67
	v_mul_f32_e32 v64, v64, v66
	ds_write2st64_b32 v162, v68, v69 offset0:10 offset1:11
	ds_write2st64_b32 v162, v65, v64 offset0:12 offset1:13
	s_waitcnt lgkmcnt(0)
	s_waitcnt vmcnt(8)
	s_barrier
	s_cbranch_vccnz .LBB0_430
